# split MERGE units 18/30 K-tiles (hooked half shorter) + MERGE hook/epilogue gate loads deeper in flight
# speedup vs baseline: 1.0050x; 1.0050x over previous
; #define PG8_WAIT_V(n) asm volatile("s_waitcnt vmcnt(" #n ")" ::: "memory")
; #define PG8_BAR __builtin_amdgcn_s_barrier()
; template <class Epi, class Sched, bool ALIGN_EPI = false, bool SP2 = false>
; __device__ __forceinline__ void gemm_phase(PG8_LAS unsigned char* lds, const Gemm g, const Sched& S, const Epi& E) {
;     int tid_ = threadIdx.x; asm volatile("" : "+v"(tid_)); const int tid = tid_, wid = __builtin_amdgcn_readfirstlane(tid >> 6), lane = tid & 63, wr = wid >> 2, wc = wid & 3, fr = lane & 15, fq = lane >> 4;
;     const int K = g.ld, nt = g.K / BK;
;     unsigned voffA[2], voffB[2];
; #pragma unroll
;     for (int i = 0; i < 2; ++i) { int R, C; stage_rc(tid * 16 + i * 8192, R, C); const int Rb = Epi::PERM ? ((R & ~31) + perm32(R & 31)) : R;
;         voffA[i] = (unsigned)(R * K + C) * 2u; voffB[i] = (unsigned)(Rb * K + C) * 2u; }
;     const size_t kstep = (size_t)(BK * 2);
;     const size_t hstep = (size_t)HALF * K * 2;
;     const size_t tstep = 2 * hstep;
;     const unsigned ldsw = (unsigned)wid * 1024u;
;     const int aoff = lds_byte(wr * 64 + fr, fq * 8), boff = lds_byte(wc * 32 + fr, fq * 8);
;     ...
;     Unit cur, nxt; int ui = 0;
;     if (!S.next(0, cur)) return;
;     f32x4 acc[2][2][4][2];
; #pragma unroll
;     for (int a = 0; a < 2; ++a)
; #pragma unroll
;         for (int b = 0; b < 2; ++b)
; #pragma unroll
;             for (int m = 0; m < 4; ++m)
; #pragma unroll
;                 for (int n = 0; n < 2; ++n) acc[a][b][m][n] = (f32x4){0.f, 0.f, 0.f, 0.f};
;     bf16x8 At[4][2], B0[2][2], B1[2][2];
;     const char* cA = (const char*)g.A + (size_t)cur.pm * tstep; const char* cB = (const char*)g.Bt + (size_t)cur.pn * tstep;
;     S.a_ready(cur);
;     if constexpr (SP2) {
;         PG8_STAGE(PG8_SB(0, 0), cB, voffB); PG8_STAGE(PG8_SB(0, 1), cB + hstep, voffB); PG8_STAGE(PG8_SA(0, 0), cA, voffA); PG8_STAGE(PG8_SA(0, 1), cA + hstep, voffA);
;         if (wr == 1) PG8_BAR;
;         PG8_WAIT_V(2); PG8_BAR;
;         PG8_STAGE(PG8_SB(1, 0), cB + kstep, voffB); PG8_STAGE(PG8_SA(1, 0), cA + kstep, voffA); PG8_STAGE(PG8_SB(1, 1), cB + hstep + kstep, voffB);
;         PG8_WAIT_V(6); PG8_BAR;
;     } else {
;         PG8_STAGE(PG8_SB(0, 0), cB, voffB); PG8_STAGE(PG8_SA(0, 0), cA, voffA); PG8_STAGE(PG8_SB(0, 1), cB + hstep, voffB); PG8_STAGE(PG8_SA(0, 1), cA + hstep, voffA);
;         if (wr == 1) PG8_BAR;
;         PG8_WAIT_V(4); PG8_BAR;
.LBB0_743:
	v_mov_b32_e32 v17, v193
	s_cmp_lt_i32 s95, 1
	v_readfirstlane_b32 s3, v17
	s_cbranch_scc1 .LBB0_767
	s_waitcnt vmcnt(1)
	v_lshlrev_b32_e32 v2, 4, v17
	v_add_u32_e32 v3, 0x2000, v2
	v_ashrrev_i32_e32 v0, 31, v3
	v_lshrrev_b32_e32 v0, 22, v0
	v_add_u32_e32 v0, v3, v0
	v_ashrrev_i32_e32 v0, 10, v0
	v_mul_i32_i24_e32 v4, 0x400, v0
	v_sub_u32_e32 v3, v3, v4
	v_lshrrev_b32_e32 v4, 4, v3
	s_ashr_i32 s2, s3, 6
	v_bitop3_b32 v3, v4, v3, 32 bitop3:0x6c
	s_ashr_i32 s20, s3, 8
	s_lshl_b32 s14, s2, 10
	s_ashr_i32 s15, s13, 3
	s_and_b32 s16, s13, 7
	v_ashrrev_i32_e32 v4, 31, v3
	s_cmp_lg_u32 s5, 1
	v_lshrrev_b32_e32 v4, 26, v4
	s_cselect_b64 s[38:39], -1, 0
	v_add_u32_e32 v4, v3, v4
	v_lshlrev_b32_e32 v5, 3, v0
	s_and_b64 s[6:7], s[38:39], exec
	v_ashrrev_i32_e32 v10, 6, v4
	v_and_b32_e32 v5, -16, v5
	s_cselect_b32 s5, 0, 0x900
	v_readlane_b32 s6, v248, 33
	v_add_u32_e32 v5, v10, v5
	s_add_u32 s17, s6, s5
	v_readlane_b32 s6, v248, 35
	v_and_b32_e32 v6, 3, v10
	s_mov_b32 s21, 0x3fffe0
	v_lshrrev_b32_e32 v7, 2, v5
	v_lshlrev_b32_e32 v8, 1, v5
	v_and_b32_e32 v4, 0xc0, v4
	s_addc_u32 s33, s6, 0
	v_readlane_b32 s6, v248, 34
	v_and_or_b32 v6, v5, s21, v6
	v_and_b32_e32 v7, 4, v7
	v_and_b32_e32 v8, 24, v8
	v_sub_u32_e32 v3, v3, v4
	s_add_u32 s6, s6, s5
	v_readlane_b32 s5, v248, 37
	v_or3_b32 v6, v6, v7, v8
	v_lshlrev_b32_e32 v7, 5, v0
	v_ashrrev_i16_sdwa v3, v216, sext(v3) dst_sel:DWORD dst_unused:UNUSED_PAD src0_sel:DWORD src1_sel:BYTE_0
	s_addc_u32 s7, s5, 0
	v_and_b32_e32 v11, 32, v7
	v_bfe_i32 v12, v3, 0, 16
	s_movk_i32 s5, 0xc00
	v_mul_u32_u24_e32 v6, 0xc00, v6
	v_add_u32_e32 v3, v11, v12
	v_mul_lo_u32 v4, v5, s5
	v_add_lshl_u32 v168, v6, v3, 1
	v_add_lshl_u32 v170, v3, v4, 1
	v_bfe_i32 v3, v17, 27, 1
	v_lshrrev_b32_e32 v3, 22, v3
	v_add_u32_e32 v3, v2, v3
	v_and_b32_e32 v3, 0xfffffc00, v3
	v_sub_u32_e32 v2, v2, v3
	v_lshrrev_b32_e32 v3, 4, v2
	v_ashrrev_i32_e32 v4, 31, v17
	v_bitop3_b32 v2, v3, v2, 32 bitop3:0x6c
	v_lshrrev_b32_e32 v4, 26, v4
	v_ashrrev_i32_e32 v3, 31, v2
	v_add_u32_e32 v4, v17, v4
	v_lshrrev_b32_e32 v3, 26, v3
	v_ashrrev_i32_e32 v14, 6, v4
	v_add_u32_e32 v3, v2, v3
	v_lshlrev_b32_e32 v4, 3, v14
	v_ashrrev_i32_e32 v13, 6, v3
	v_and_b32_e32 v4, -16, v4
	v_add_u32_e32 v4, v13, v4
	v_and_b32_e32 v5, 3, v13
	v_lshrrev_b32_e32 v6, 2, v4
	v_lshlrev_b32_e32 v7, 1, v4
	v_and_b32_e32 v3, 0xc0, v3
	v_and_or_b32 v5, v4, s21, v5
	v_and_b32_e32 v6, 4, v6
	v_and_b32_e32 v7, 24, v7
	v_sub_u32_e32 v2, v2, v3
	v_or3_b32 v5, v5, v6, v7
	v_lshlrev_b32_e32 v6, 5, v14
	v_ashrrev_i16_sdwa v2, v216, sext(v2) dst_sel:DWORD dst_unused:UNUSED_PAD src0_sel:DWORD src1_sel:BYTE_0
	v_mul_lo_u32 v3, v4, s5
	s_mul_i32 s5, s16, 0x180000
	s_mov_b64 s[66:67], s[90:91]
	v_and_b32_e32 v15, 32, v6
	v_bfe_i32 v16, v2, 0, 16
	s_add_u32 s90, s6, s5
	v_mul_u32_u24_e32 v5, 0xc00, v5
	v_add_u32_e32 v2, v15, v16
	s_addc_u32 s91, s7, 0
	s_add_i32 s5, s14, 0
	v_add_lshl_u32 v172, v5, v2, 1
	s_add_i32 m0, s5, 0x10000
	s_mul_i32 s30, s15, 0x180000
	global_load_lds_dwordx4 v172, s[90:91]
	s_add_i32 m0, s5, 0x12000
	s_add_u32 s28, s90, 0xc0000
	global_load_lds_dwordx4 v168, s[90:91]
	s_addc_u32 s29, s91, 0
	s_add_i32 m0, s5, 0x14000
	s_mul_hi_i32 s21, s15, 0x180000
	global_load_lds_dwordx4 v172, s[28:29]
	s_add_i32 m0, s5, 0x16000
	s_add_u32 s52, s17, s30
	s_addc_u32 s53, s33, s21
	s_add_i32 s34, s5, 0x2000
	v_add_lshl_u32 v174, v2, v3, 1
	global_load_lds_dwordx4 v168, s[28:29]
	s_mov_b32 m0, s5
	s_add_u32 s30, s52, 0xc0000
	global_load_lds_dwordx4 v174, s[52:53]
	s_mov_b32 m0, s34
	s_addc_u32 s31, s53, 0
	s_add_i32 s28, s5, 0x4000
	global_load_lds_dwordx4 v170, s[52:53]
	s_mov_b32 m0, s28
	s_add_i32 s29, s5, 0x6000
	global_load_lds_dwordx4 v174, s[30:31]
	s_mov_b32 m0, s29
	v_mov_b32_e32 v173, v1
	global_load_lds_dwordx4 v170, s[30:31]
	v_mov_b32_e32 v169, v1
	v_mov_b32_e32 v175, v1
	v_mov_b32_e32 v171, v1
	s_cmp_eq_u32 s20, 1
	s_mov_b64 s[68:69], s[56:57]
	s_mov_b64 s[42:43], s[78:79]
	v_lshl_add_u64 v[8:9], s[90:91], 0, v[172:173]
	v_lshl_add_u64 v[6:7], s[90:91], 0, v[168:169]
	v_lshl_add_u64 v[2:3], s[52:53], 0, v[174:175]
	s_cselect_b64 s[40:41], -1, 0
	s_cmp_lg_u32 s20, 1
	v_lshl_add_u64 v[4:5], s[52:53], 0, v[170:171]
	s_cbranch_scc1 .LBB0_746
	s_barrier
.LBB0_746:
	v_lshrrev_b32_e32 v19, 1, v17
	v_and_b32_e32 v19, 24, v19
	s_lshl_b32 s2, s2, 5
	v_and_b32_e32 v18, 15, v17
	v_lshlrev_b32_e32 v20, 1, v19
	v_lshlrev_b32_e32 v17, 2, v17
	s_and_b32 s36, s2, 0x60
	v_lshl_or_b32 v190, s20, 6, v18
	v_lshl_or_b32 v18, v18, 6, v20
	s_lshl_b32 s20, s20, 13
	v_and_b32_e32 v17, 32, v17
	s_lshl_b32 s2, s36, 7
	v_bitop3_b32 v20, v18, s20, v17 bitop3:0xde
	s_and_b64 s[20:21], exec, s[48:49]
	s_cselect_b32 s30, 48, 18
	s_cmp_lg_u64 s[38:39], 0
	s_cselect_b32 s30, s30, 30
	s_add_i32 m0, s5, 0x18000
	v_lshl_add_u64 v[8:9], v[8:9], 0, s[54:55]
	v_bitop3_b32 v191, v18, s2, v17 bitop3:0xde
	s_waitcnt vmcnt(2)
	s_barrier
	global_load_lds_dwordx4 v[8:9], off
	v_lshl_add_u64 v[6:7], v[6:7], 0, s[54:55]
	s_add_i32 m0, s5, 0x1a000
	s_add_i32 s31, s5, 0x8000
	s_add_i32 s2, s5, 0xa000
	global_load_lds_dwordx4 v[6:7], off
	v_lshl_add_u64 v[2:3], v[2:3], 0, s[54:55]
	s_mov_b32 m0, s31
	s_add_u32 s20, s90, 0xc0080
	global_load_lds_dwordx4 v[2:3], off
	v_lshl_add_u64 v[2:3], v[4:5], 0, s[54:55]
	s_mov_b32 m0, s2
	s_addc_u32 s21, s91, 0
	global_load_lds_dwordx4 v[2:3], off
	s_add_i32 m0, s5, 0x1c000
	v_lshl_add_u64 v[2:3], s[20:21], 0, v[172:173]
	global_load_lds_dwordx4 v[2:3], off
	v_lshl_add_u64 v[2:3], s[20:21], 0, v[168:169]
	s_add_i32 m0, s5, 0x1e000
	s_movk_i32 s37, 0xc00
	global_load_lds_dwordx4 v[2:3], off
	v_or_b32_e32 v192, s36, v19
	v_lshrrev_b32_e32 v2, 1, v0
	v_mul_lo_u32 v0, v10, s37
	s_mov_b32 s36, 0xc000
	v_mad_u64_u32 v[2:3], s[20:21], v2, s36, v[0:1]
	v_or_b32_e32 v0, v2, v11
	v_add_lshl_u32 v176, v0, v12, 1
	v_lshrrev_b32_e32 v2, 1, v14
	v_mul_lo_u32 v0, v13, s37
	s_waitcnt vmcnt(6)
	s_cmpk_lt_u32 s3, 0x100
	v_mad_u64_u32 v[2:3], s[20:21], v2, s36, v[0:1]
	s_cselect_b64 s[74:75], -1, 0
	v_or_b32_e32 v0, v2, v15
	s_lshl_b32 s20, s30, 7
	s_add_i32 s3, s95, -1
	v_mov_b32_e32 v177, v1
	v_add_lshl_u32 v178, v0, v16, 1
	v_mov_b32_e32 v179, v1
	s_add_i32 s36, s20, 0xffffff00
	s_mov_b32 s37, 0
	v_add_u32_e32 v194, 0, v20
	s_mov_b64 s[86:87], s[52:53]
	s_barrier
	s_branch .LBB0_749

;     __device__ __forceinline__ void hook(f32x4 (&acc)[2][2][4][2], const Unit& u, int wr, int wc, int fr, int fq) const {
;         int row0 = u.pm * BM + wr * 64 + fr, col0 = u.pn * BM + wc * 32 + 8 * fq;
;         asm volatile("" : "+v"(row0), "+v"(col0));
;         u32x4 ga[2][2], gb[2][2];
; #pragma unroll
;         for (int bj = 0; bj < 2; ++bj) { const bf16_t* gp = G + (size_t)row0 * ldg + col0 + bj * HALF; ga[0][bj] = *(const u32x4*)(gp + 6144); gb[0][bj] = *(const u32x4*)(gp + 8192); }
; #pragma unroll
;         for (int g = 0; g < 8; ++g) { const int ai = g >> 2, m = g & 3, cb = g & 1, nb_ = cb ^ 1;
;             if (g < 7) { const int an = (g + 1) >> 2, mn = (g + 1) & 3;
; #pragma unroll
;                 for (int bj = 0; bj < 2; ++bj) { const bf16_t* gp = G + (size_t)(row0 + an * HALF + mn * 16) * ldg + col0 + bj * HALF; ga[nb_][bj] = *(const u32x4*)(gp + 6144); gb[nb_][bj] = *(const u32x4*)(gp + 8192); } }
; #pragma unroll
;             for (int bj = 0; bj < 2; ++bj) { f32x4 a0, a1, b0, b1; unpack_bf16x8(ga[cb][bj], a0, a1); unpack_bf16x8(gb[cb][bj], b0, b1);
; #pragma unroll
;                 for (int j = 0; j < 4; ++j) { a0[j] = a0[j] * __builtin_amdgcn_rcpf(fmaxf(b0[j], 1e-30f)); a1[j] = a1[j] * __builtin_amdgcn_rcpf(fmaxf(b1[j], 1e-30f)); }
;                 acc[ai][bj][m][0] = acc[ai][bj][m][0] * a0; acc[ai][bj][m][1] = acc[ai][bj][m][1] * a1; }
;             asm volatile("" ::: "memory"); }
.LBB0_755:
	s_cmpk_eq_i32 s90, 0x800
	s_cselect_b64 s[92:93], -1, 0
	s_and_b64 s[92:93], s[38:39], s[92:93]
	s_andn2_b64 vcc, exec, s[92:93]
	s_cbranch_vccnz .LBB0_754
	v_mul_u32_u24_e32 v2, 0x5000, v180
	v_lshl_add_u32 v2, v182, 1, v2
	s_add_u32 s98, s8, 0x3000
	s_addc_u32 s99, s9, 0
	s_add_u32 s100, s8, 0x4000
	s_addc_u32 s101, s9, 0
	s_nop 1
	global_load_dwordx4 v[132:135], v2, s[98:99]
	global_load_dwordx4 v[136:139], v2, s[100:101]
	global_load_dwordx4 v[140:143], v2, s[98:99] offset:256
	global_load_dwordx4 v[144:147], v2, s[100:101] offset:256
	v_add_u32_e32 v2, 0x50000, v2
	global_load_dwordx4 v[148:151], v2, s[98:99]
	global_load_dwordx4 v[152:155], v2, s[100:101]
	global_load_dwordx4 v[156:159], v2, s[98:99] offset:256
	global_load_dwordx4 v[160:163], v2, s[100:101] offset:256
	v_add_u32_e32 v2, 0x50000, v2
	global_load_dwordx4 v[196:199], v2, s[98:99]
	global_load_dwordx4 v[210:213], v2, s[100:101]
	global_load_dwordx4 v[224:227], v2, s[98:99] offset:256
	global_load_dwordx4 v[228:231], v2, s[100:101] offset:256
	v_add_u32_e32 v2, 0x50000, v2
	global_load_dwordx4 v[232:235], v2, s[98:99]
	global_load_dwordx4 v[236:239], v2, s[100:101]
	global_load_dwordx4 v[240:243], v2, s[98:99] offset:256
	global_load_dwordx4 v[244:247], v2, s[100:101] offset:256
	v_add_u32_e32 v2, 0x190000, v2
	s_waitcnt vmcnt(14)
	v_lshlrev_b32_e32 v188, 16, v136
	v_and_b32_e32 v189, 0xffff0000, v136
	v_lshlrev_b32_e32 v200, 16, v137
	v_and_b32_e32 v201, 0xffff0000, v137
	v_max_f32_e32 v188, v188, v188
	v_max_f32_e32 v189, v189, v189
	v_max_f32_e32 v200, v200, v200
	v_max_f32_e32 v201, v201, v201
	v_max_f32_e32 v188, 0xda24260, v188
	v_max_f32_e32 v189, 0xda24260, v189
	v_max_f32_e32 v200, 0xda24260, v200
	v_max_f32_e32 v201, 0xda24260, v201
	v_rcp_f32_e32 v188, v188
	v_rcp_f32_e32 v189, v189
	v_rcp_f32_e32 v200, v200
	v_rcp_f32_e32 v201, v201
	v_lshlrev_b32_e32 v204, 16, v132
	v_and_b32_e32 v205, 0xffff0000, v132
	v_lshlrev_b32_e32 v214, 16, v133
	v_and_b32_e32 v215, 0xffff0000, v133
	v_pk_mul_f32 v[188:189], v[188:189], v[204:205]
	v_pk_mul_f32 v[200:201], v[200:201], v[214:215]
	v_pk_mul_f32 v[120:121], v[120:121], v[188:189]
	v_pk_mul_f32 v[122:123], v[122:123], v[200:201]
	v_lshlrev_b32_e32 v188, 16, v138
	v_and_b32_e32 v189, 0xffff0000, v138
	v_lshlrev_b32_e32 v200, 16, v139
	v_and_b32_e32 v201, 0xffff0000, v139
	v_max_f32_e32 v188, v188, v188
	v_max_f32_e32 v189, v189, v189
	v_max_f32_e32 v200, v200, v200
	v_max_f32_e32 v201, v201, v201
	v_max_f32_e32 v188, 0xda24260, v188
	v_max_f32_e32 v189, 0xda24260, v189
	v_max_f32_e32 v200, 0xda24260, v200
	v_max_f32_e32 v201, 0xda24260, v201
	v_rcp_f32_e32 v188, v188
	v_rcp_f32_e32 v189, v189
	v_rcp_f32_e32 v200, v200
	v_rcp_f32_e32 v201, v201
	v_lshlrev_b32_e32 v204, 16, v134
	v_and_b32_e32 v205, 0xffff0000, v134
	v_lshlrev_b32_e32 v214, 16, v135
	v_and_b32_e32 v215, 0xffff0000, v135
	v_pk_mul_f32 v[188:189], v[188:189], v[204:205]
	v_pk_mul_f32 v[200:201], v[200:201], v[214:215]
	v_pk_mul_f32 v[116:117], v[116:117], v[188:189]
	v_pk_mul_f32 v[118:119], v[118:119], v[200:201]
	s_waitcnt vmcnt(12)
	v_lshlrev_b32_e32 v188, 16, v144
	v_and_b32_e32 v189, 0xffff0000, v144
	v_lshlrev_b32_e32 v200, 16, v145
	v_and_b32_e32 v201, 0xffff0000, v145
	v_max_f32_e32 v188, v188, v188
	v_max_f32_e32 v189, v189, v189
	v_max_f32_e32 v200, v200, v200
	v_max_f32_e32 v201, v201, v201
	v_max_f32_e32 v188, 0xda24260, v188
	v_max_f32_e32 v189, 0xda24260, v189
	v_max_f32_e32 v200, 0xda24260, v200
	v_max_f32_e32 v201, 0xda24260, v201
	v_rcp_f32_e32 v188, v188
	v_rcp_f32_e32 v189, v189
	v_rcp_f32_e32 v200, v200
	v_rcp_f32_e32 v201, v201
	v_lshlrev_b32_e32 v204, 16, v140
	v_and_b32_e32 v205, 0xffff0000, v140
	v_lshlrev_b32_e32 v214, 16, v141
	v_and_b32_e32 v215, 0xffff0000, v141
	v_pk_mul_f32 v[188:189], v[188:189], v[204:205]
	v_pk_mul_f32 v[200:201], v[200:201], v[214:215]
	v_pk_mul_f32 v[128:129], v[128:129], v[188:189]
	v_pk_mul_f32 v[130:131], v[130:131], v[200:201]
	v_lshlrev_b32_e32 v188, 16, v146
	v_and_b32_e32 v189, 0xffff0000, v146
	v_lshlrev_b32_e32 v200, 16, v147
	v_and_b32_e32 v201, 0xffff0000, v147
	v_max_f32_e32 v188, v188, v188
	v_max_f32_e32 v189, v189, v189
	v_max_f32_e32 v200, v200, v200
	v_max_f32_e32 v201, v201, v201
	v_max_f32_e32 v188, 0xda24260, v188
	v_max_f32_e32 v189, 0xda24260, v189
	v_max_f32_e32 v200, 0xda24260, v200
	v_max_f32_e32 v201, 0xda24260, v201
	v_rcp_f32_e32 v188, v188
	v_rcp_f32_e32 v189, v189
	v_rcp_f32_e32 v200, v200
	v_rcp_f32_e32 v201, v201
	v_lshlrev_b32_e32 v204, 16, v142
	v_and_b32_e32 v205, 0xffff0000, v142
	v_lshlrev_b32_e32 v214, 16, v143
	v_and_b32_e32 v215, 0xffff0000, v143
	v_pk_mul_f32 v[188:189], v[188:189], v[204:205]
	v_pk_mul_f32 v[200:201], v[200:201], v[214:215]
	v_pk_mul_f32 v[124:125], v[124:125], v[188:189]
	v_pk_mul_f32 v[126:127], v[126:127], v[200:201]
	global_load_dwordx4 v[132:135], v2, s[98:99]
	global_load_dwordx4 v[136:139], v2, s[100:101]
	global_load_dwordx4 v[140:143], v2, s[98:99] offset:256
	global_load_dwordx4 v[144:147], v2, s[100:101] offset:256
	v_add_u32_e32 v2, 0x50000, v2
	s_waitcnt vmcnt(14)
;     __device__ __forceinline__ void hook(f32x4 (&acc)[2][2][4][2], const Unit& u, int wr, int wc, int fr, int fq) const {
;     ...
;         for (int g = 0; g < 8; ++g) { const int ai = g >> 2, m = g & 3, cb = g & 1, nb_ = cb ^ 1;
;             if (g < 7) { const int an = (g + 1) >> 2, mn = (g + 1) & 3;
; #pragma unroll
;                 for (int bj = 0; bj < 2; ++bj) { const bf16_t* gp = G + (size_t)(row0 + an * HALF + mn * 16) * ldg + col0 + bj * HALF; ga[nb_][bj] = *(const u32x4*)(gp + 6144); gb[nb_][bj] = *(const u32x4*)(gp + 8192); } }
; #pragma unroll
;             for (int bj = 0; bj < 2; ++bj) { f32x4 a0, a1, b0, b1; unpack_bf16x8(ga[cb][bj], a0, a1); unpack_bf16x8(gb[cb][bj], b0, b1);
; #pragma unroll
;                 for (int j = 0; j < 4; ++j) { a0[j] = a0[j] * __builtin_amdgcn_rcpf(fmaxf(b0[j], 1e-30f)); a1[j] = a1[j] * __builtin_amdgcn_rcpf(fmaxf(b1[j], 1e-30f)); }
;                 acc[ai][bj][m][0] = acc[ai][bj][m][0] * a0; acc[ai][bj][m][1] = acc[ai][bj][m][1] * a1; }
;             asm volatile("" ::: "memory"); }
	v_lshlrev_b32_e32 v188, 16, v152
	v_and_b32_e32 v189, 0xffff0000, v152
	v_lshlrev_b32_e32 v200, 16, v153
	v_and_b32_e32 v201, 0xffff0000, v153
	v_max_f32_e32 v188, v188, v188
	v_max_f32_e32 v189, v189, v189
	v_max_f32_e32 v200, v200, v200
	v_max_f32_e32 v201, v201, v201
	v_max_f32_e32 v188, 0xda24260, v188
	v_max_f32_e32 v189, 0xda24260, v189
	v_max_f32_e32 v200, 0xda24260, v200
	v_max_f32_e32 v201, 0xda24260, v201
	v_rcp_f32_e32 v188, v188
	v_rcp_f32_e32 v189, v189
	v_rcp_f32_e32 v200, v200
	v_rcp_f32_e32 v201, v201
	v_lshlrev_b32_e32 v204, 16, v148
	v_and_b32_e32 v205, 0xffff0000, v148
	v_lshlrev_b32_e32 v214, 16, v149
	v_and_b32_e32 v215, 0xffff0000, v149
	v_pk_mul_f32 v[188:189], v[188:189], v[204:205]
	v_pk_mul_f32 v[200:201], v[200:201], v[214:215]
	v_pk_mul_f32 v[112:113], v[112:113], v[188:189]
	v_pk_mul_f32 v[114:115], v[114:115], v[200:201]
	v_lshlrev_b32_e32 v188, 16, v154
	v_and_b32_e32 v189, 0xffff0000, v154
	v_lshlrev_b32_e32 v200, 16, v155
	v_and_b32_e32 v201, 0xffff0000, v155
	v_max_f32_e32 v188, v188, v188
	v_max_f32_e32 v189, v189, v189
	v_max_f32_e32 v200, v200, v200
	v_max_f32_e32 v201, v201, v201
	v_max_f32_e32 v188, 0xda24260, v188
	v_max_f32_e32 v189, 0xda24260, v189
	v_max_f32_e32 v200, 0xda24260, v200
	v_max_f32_e32 v201, 0xda24260, v201
	v_rcp_f32_e32 v188, v188
	v_rcp_f32_e32 v189, v189
	v_rcp_f32_e32 v200, v200
	v_rcp_f32_e32 v201, v201
	v_lshlrev_b32_e32 v204, 16, v150
	v_and_b32_e32 v205, 0xffff0000, v150
	v_lshlrev_b32_e32 v214, 16, v151
	v_and_b32_e32 v215, 0xffff0000, v151
	v_pk_mul_f32 v[188:189], v[188:189], v[204:205]
	v_pk_mul_f32 v[200:201], v[200:201], v[214:215]
	v_pk_mul_f32 v[108:109], v[108:109], v[188:189]
	v_pk_mul_f32 v[110:111], v[110:111], v[200:201]
	s_waitcnt vmcnt(12)
	v_lshlrev_b32_e32 v188, 16, v160
	v_and_b32_e32 v189, 0xffff0000, v160
	v_lshlrev_b32_e32 v200, 16, v161
	v_and_b32_e32 v201, 0xffff0000, v161
	v_max_f32_e32 v188, v188, v188
	v_max_f32_e32 v189, v189, v189
	v_max_f32_e32 v200, v200, v200
	v_max_f32_e32 v201, v201, v201
	v_max_f32_e32 v188, 0xda24260, v188
	v_max_f32_e32 v189, 0xda24260, v189
	v_max_f32_e32 v200, 0xda24260, v200
	v_max_f32_e32 v201, 0xda24260, v201
	v_rcp_f32_e32 v188, v188
	v_rcp_f32_e32 v189, v189
	v_rcp_f32_e32 v200, v200
	v_rcp_f32_e32 v201, v201
	v_lshlrev_b32_e32 v204, 16, v156
	v_and_b32_e32 v205, 0xffff0000, v156
	v_lshlrev_b32_e32 v214, 16, v157
	v_and_b32_e32 v215, 0xffff0000, v157
	v_pk_mul_f32 v[188:189], v[188:189], v[204:205]
	v_pk_mul_f32 v[200:201], v[200:201], v[214:215]
	v_pk_mul_f32 v[104:105], v[104:105], v[188:189]
	v_pk_mul_f32 v[106:107], v[106:107], v[200:201]
	v_lshlrev_b32_e32 v188, 16, v162
	v_and_b32_e32 v189, 0xffff0000, v162
	v_lshlrev_b32_e32 v200, 16, v163
	v_and_b32_e32 v201, 0xffff0000, v163
	v_max_f32_e32 v188, v188, v188
	v_max_f32_e32 v189, v189, v189
	v_max_f32_e32 v200, v200, v200
	v_max_f32_e32 v201, v201, v201
	v_max_f32_e32 v188, 0xda24260, v188
	v_max_f32_e32 v189, 0xda24260, v189
	v_max_f32_e32 v200, 0xda24260, v200
	v_max_f32_e32 v201, 0xda24260, v201
	v_rcp_f32_e32 v188, v188
	v_rcp_f32_e32 v189, v189
	v_rcp_f32_e32 v200, v200
	v_rcp_f32_e32 v201, v201
	v_lshlrev_b32_e32 v204, 16, v158
	v_and_b32_e32 v205, 0xffff0000, v158
	v_lshlrev_b32_e32 v214, 16, v159
	v_and_b32_e32 v215, 0xffff0000, v159
	v_pk_mul_f32 v[188:189], v[188:189], v[204:205]
	v_pk_mul_f32 v[200:201], v[200:201], v[214:215]
	v_pk_mul_f32 v[100:101], v[100:101], v[188:189]
	v_pk_mul_f32 v[102:103], v[102:103], v[200:201]
	global_load_dwordx4 v[148:151], v2, s[98:99]
	global_load_dwordx4 v[152:155], v2, s[100:101]
	global_load_dwordx4 v[156:159], v2, s[98:99] offset:256
	global_load_dwordx4 v[160:163], v2, s[100:101] offset:256
	v_add_u32_e32 v2, 0x50000, v2
	s_waitcnt vmcnt(14)
	v_lshlrev_b32_e32 v188, 16, v210
	v_and_b32_e32 v189, 0xffff0000, v210
	v_lshlrev_b32_e32 v200, 16, v211
	v_and_b32_e32 v201, 0xffff0000, v211
	v_max_f32_e32 v188, v188, v188
	v_max_f32_e32 v189, v189, v189
	v_max_f32_e32 v200, v200, v200
	v_max_f32_e32 v201, v201, v201
	v_max_f32_e32 v188, 0xda24260, v188
	v_max_f32_e32 v189, 0xda24260, v189
	v_max_f32_e32 v200, 0xda24260, v200
	v_max_f32_e32 v201, 0xda24260, v201
	v_rcp_f32_e32 v188, v188
	v_rcp_f32_e32 v189, v189
	v_rcp_f32_e32 v200, v200
	v_rcp_f32_e32 v201, v201
	v_lshlrev_b32_e32 v204, 16, v196
	v_and_b32_e32 v205, 0xffff0000, v196
	v_lshlrev_b32_e32 v214, 16, v197
	v_and_b32_e32 v215, 0xffff0000, v197
	v_pk_mul_f32 v[188:189], v[188:189], v[204:205]
	v_pk_mul_f32 v[200:201], v[200:201], v[214:215]
	v_pk_mul_f32 v[96:97], v[96:97], v[188:189]
	v_pk_mul_f32 v[98:99], v[98:99], v[200:201]
	v_lshlrev_b32_e32 v188, 16, v212
	v_and_b32_e32 v189, 0xffff0000, v212
	v_lshlrev_b32_e32 v200, 16, v213
	v_and_b32_e32 v201, 0xffff0000, v213
	v_max_f32_e32 v188, v188, v188
	v_max_f32_e32 v189, v189, v189
	v_max_f32_e32 v200, v200, v200
	v_max_f32_e32 v201, v201, v201
	v_max_f32_e32 v188, 0xda24260, v188
	v_max_f32_e32 v189, 0xda24260, v189
	v_max_f32_e32 v200, 0xda24260, v200
	v_max_f32_e32 v201, 0xda24260, v201
	v_rcp_f32_e32 v188, v188
	v_rcp_f32_e32 v189, v189
	v_rcp_f32_e32 v200, v200
	v_rcp_f32_e32 v201, v201
	v_lshlrev_b32_e32 v204, 16, v198
	v_and_b32_e32 v205, 0xffff0000, v198
	v_lshlrev_b32_e32 v214, 16, v199
	v_and_b32_e32 v215, 0xffff0000, v199
	v_pk_mul_f32 v[188:189], v[188:189], v[204:205]
	v_pk_mul_f32 v[200:201], v[200:201], v[214:215]
	v_pk_mul_f32 v[92:93], v[92:93], v[188:189]
	v_pk_mul_f32 v[94:95], v[94:95], v[200:201]
	s_waitcnt vmcnt(12)
;     __device__ __forceinline__ void hook(f32x4 (&acc)[2][2][4][2], const Unit& u, int wr, int wc, int fr, int fq) const {
;     ...
;         for (int g = 0; g < 8; ++g) { const int ai = g >> 2, m = g & 3, cb = g & 1, nb_ = cb ^ 1;
;             if (g < 7) { const int an = (g + 1) >> 2, mn = (g + 1) & 3;
; #pragma unroll
;                 for (int bj = 0; bj < 2; ++bj) { const bf16_t* gp = G + (size_t)(row0 + an * HALF + mn * 16) * ldg + col0 + bj * HALF; ga[nb_][bj] = *(const u32x4*)(gp + 6144); gb[nb_][bj] = *(const u32x4*)(gp + 8192); } }
; #pragma unroll
;             for (int bj = 0; bj < 2; ++bj) { f32x4 a0, a1, b0, b1; unpack_bf16x8(ga[cb][bj], a0, a1); unpack_bf16x8(gb[cb][bj], b0, b1);
; #pragma unroll
;                 for (int j = 0; j < 4; ++j) { a0[j] = a0[j] * __builtin_amdgcn_rcpf(fmaxf(b0[j], 1e-30f)); a1[j] = a1[j] * __builtin_amdgcn_rcpf(fmaxf(b1[j], 1e-30f)); }
;                 acc[ai][bj][m][0] = acc[ai][bj][m][0] * a0; acc[ai][bj][m][1] = acc[ai][bj][m][1] * a1; }
;             asm volatile("" ::: "memory"); }
	v_lshlrev_b32_e32 v188, 16, v228
	v_and_b32_e32 v189, 0xffff0000, v228
	v_lshlrev_b32_e32 v200, 16, v229
	v_and_b32_e32 v201, 0xffff0000, v229
	v_max_f32_e32 v188, v188, v188
	v_max_f32_e32 v189, v189, v189
	v_max_f32_e32 v200, v200, v200
	v_max_f32_e32 v201, v201, v201
	v_max_f32_e32 v188, 0xda24260, v188
	v_max_f32_e32 v189, 0xda24260, v189
	v_max_f32_e32 v200, 0xda24260, v200
	v_max_f32_e32 v201, 0xda24260, v201
	v_rcp_f32_e32 v188, v188
	v_rcp_f32_e32 v189, v189
	v_rcp_f32_e32 v200, v200
	v_rcp_f32_e32 v201, v201
	v_lshlrev_b32_e32 v204, 16, v224
	v_and_b32_e32 v205, 0xffff0000, v224
	v_lshlrev_b32_e32 v214, 16, v225
	v_and_b32_e32 v215, 0xffff0000, v225
	v_pk_mul_f32 v[188:189], v[188:189], v[204:205]
	v_pk_mul_f32 v[200:201], v[200:201], v[214:215]
	v_pk_mul_f32 v[88:89], v[88:89], v[188:189]
	v_pk_mul_f32 v[90:91], v[90:91], v[200:201]
	v_lshlrev_b32_e32 v188, 16, v230
	v_and_b32_e32 v189, 0xffff0000, v230
	v_lshlrev_b32_e32 v200, 16, v231
	v_and_b32_e32 v201, 0xffff0000, v231
	v_max_f32_e32 v188, v188, v188
	v_max_f32_e32 v189, v189, v189
	v_max_f32_e32 v200, v200, v200
	v_max_f32_e32 v201, v201, v201
	v_max_f32_e32 v188, 0xda24260, v188
	v_max_f32_e32 v189, 0xda24260, v189
	v_max_f32_e32 v200, 0xda24260, v200
	v_max_f32_e32 v201, 0xda24260, v201
	v_rcp_f32_e32 v188, v188
	v_rcp_f32_e32 v189, v189
	v_rcp_f32_e32 v200, v200
	v_rcp_f32_e32 v201, v201
	v_lshlrev_b32_e32 v204, 16, v226
	v_and_b32_e32 v205, 0xffff0000, v226
	v_lshlrev_b32_e32 v214, 16, v227
	v_and_b32_e32 v215, 0xffff0000, v227
	v_pk_mul_f32 v[188:189], v[188:189], v[204:205]
	v_pk_mul_f32 v[200:201], v[200:201], v[214:215]
	v_pk_mul_f32 v[84:85], v[84:85], v[188:189]
	v_pk_mul_f32 v[86:87], v[86:87], v[200:201]
	global_load_dwordx4 v[196:199], v2, s[98:99]
	global_load_dwordx4 v[210:213], v2, s[100:101]
	global_load_dwordx4 v[224:227], v2, s[98:99] offset:256
	global_load_dwordx4 v[228:231], v2, s[100:101] offset:256
	v_add_u32_e32 v2, 0x50000, v2
	s_waitcnt vmcnt(14)
	v_lshlrev_b32_e32 v188, 16, v236
	v_and_b32_e32 v189, 0xffff0000, v236
	v_lshlrev_b32_e32 v200, 16, v237
	v_and_b32_e32 v201, 0xffff0000, v237
	v_max_f32_e32 v188, v188, v188
	v_max_f32_e32 v189, v189, v189
	v_max_f32_e32 v200, v200, v200
	v_max_f32_e32 v201, v201, v201
	v_max_f32_e32 v188, 0xda24260, v188
	v_max_f32_e32 v189, 0xda24260, v189
	v_max_f32_e32 v200, 0xda24260, v200
	v_max_f32_e32 v201, 0xda24260, v201
	v_rcp_f32_e32 v188, v188
	v_rcp_f32_e32 v189, v189
	v_rcp_f32_e32 v200, v200
	v_rcp_f32_e32 v201, v201
	v_lshlrev_b32_e32 v204, 16, v232
	v_and_b32_e32 v205, 0xffff0000, v232
	v_lshlrev_b32_e32 v214, 16, v233
	v_and_b32_e32 v215, 0xffff0000, v233
	v_pk_mul_f32 v[188:189], v[188:189], v[204:205]
	v_pk_mul_f32 v[200:201], v[200:201], v[214:215]
	v_pk_mul_f32 v[80:81], v[80:81], v[188:189]
	v_pk_mul_f32 v[82:83], v[82:83], v[200:201]
	v_lshlrev_b32_e32 v188, 16, v238
	v_and_b32_e32 v189, 0xffff0000, v238
	v_lshlrev_b32_e32 v200, 16, v239
	v_and_b32_e32 v201, 0xffff0000, v239
	v_max_f32_e32 v188, v188, v188
	v_max_f32_e32 v189, v189, v189
	v_max_f32_e32 v200, v200, v200
	v_max_f32_e32 v201, v201, v201
	v_max_f32_e32 v188, 0xda24260, v188
	v_max_f32_e32 v189, 0xda24260, v189
	v_max_f32_e32 v200, 0xda24260, v200
	v_max_f32_e32 v201, 0xda24260, v201
	v_rcp_f32_e32 v188, v188
	v_rcp_f32_e32 v189, v189
	v_rcp_f32_e32 v200, v200
	v_rcp_f32_e32 v201, v201
	v_lshlrev_b32_e32 v204, 16, v234
	v_and_b32_e32 v205, 0xffff0000, v234
	v_lshlrev_b32_e32 v214, 16, v235
	v_and_b32_e32 v215, 0xffff0000, v235
	v_pk_mul_f32 v[188:189], v[188:189], v[204:205]
	v_pk_mul_f32 v[200:201], v[200:201], v[214:215]
	v_pk_mul_f32 v[76:77], v[76:77], v[188:189]
	v_pk_mul_f32 v[78:79], v[78:79], v[200:201]
	s_waitcnt vmcnt(12)
	v_lshlrev_b32_e32 v188, 16, v244
	v_and_b32_e32 v189, 0xffff0000, v244
	v_lshlrev_b32_e32 v200, 16, v245
	v_and_b32_e32 v201, 0xffff0000, v245
	v_max_f32_e32 v188, v188, v188
	v_max_f32_e32 v189, v189, v189
	v_max_f32_e32 v200, v200, v200
	v_max_f32_e32 v201, v201, v201
	v_max_f32_e32 v188, 0xda24260, v188
	v_max_f32_e32 v189, 0xda24260, v189
	v_max_f32_e32 v200, 0xda24260, v200
	v_max_f32_e32 v201, 0xda24260, v201
	v_rcp_f32_e32 v188, v188
	v_rcp_f32_e32 v189, v189
	v_rcp_f32_e32 v200, v200
	v_rcp_f32_e32 v201, v201
	v_lshlrev_b32_e32 v204, 16, v240
	v_and_b32_e32 v205, 0xffff0000, v240
	v_lshlrev_b32_e32 v214, 16, v241
	v_and_b32_e32 v215, 0xffff0000, v241
	v_pk_mul_f32 v[188:189], v[188:189], v[204:205]
	v_pk_mul_f32 v[200:201], v[200:201], v[214:215]
	v_pk_mul_f32 v[72:73], v[72:73], v[188:189]
	v_pk_mul_f32 v[74:75], v[74:75], v[200:201]
	v_lshlrev_b32_e32 v188, 16, v246
	v_and_b32_e32 v189, 0xffff0000, v246
	v_lshlrev_b32_e32 v200, 16, v247
	v_and_b32_e32 v201, 0xffff0000, v247
	v_max_f32_e32 v188, v188, v188
	v_max_f32_e32 v189, v189, v189
	v_max_f32_e32 v200, v200, v200
	v_max_f32_e32 v201, v201, v201
	v_max_f32_e32 v188, 0xda24260, v188
	v_max_f32_e32 v189, 0xda24260, v189
	v_max_f32_e32 v200, 0xda24260, v200
	v_max_f32_e32 v201, 0xda24260, v201
	v_rcp_f32_e32 v188, v188
	v_rcp_f32_e32 v189, v189
	v_rcp_f32_e32 v200, v200
	v_rcp_f32_e32 v201, v201
	v_lshlrev_b32_e32 v204, 16, v242
	v_and_b32_e32 v205, 0xffff0000, v242
	v_lshlrev_b32_e32 v214, 16, v243
	v_and_b32_e32 v215, 0xffff0000, v243
	v_pk_mul_f32 v[188:189], v[188:189], v[204:205]
	v_pk_mul_f32 v[200:201], v[200:201], v[214:215]
	v_pk_mul_f32 v[68:69], v[68:69], v[188:189]
	v_pk_mul_f32 v[70:71], v[70:71], v[200:201]
	global_load_dwordx4 v[232:235], v2, s[98:99]
	global_load_dwordx4 v[236:239], v2, s[100:101]
	global_load_dwordx4 v[240:243], v2, s[98:99] offset:256
	global_load_dwordx4 v[244:247], v2, s[100:101] offset:256
	s_waitcnt vmcnt(14)
;     __device__ __forceinline__ void hook(f32x4 (&acc)[2][2][4][2], const Unit& u, int wr, int wc, int fr, int fq) const {
;     ...
;         for (int g = 0; g < 8; ++g) { const int ai = g >> 2, m = g & 3, cb = g & 1, nb_ = cb ^ 1;
;             if (g < 7) { const int an = (g + 1) >> 2, mn = (g + 1) & 3;
; #pragma unroll
;                 for (int bj = 0; bj < 2; ++bj) { const bf16_t* gp = G + (size_t)(row0 + an * HALF + mn * 16) * ldg + col0 + bj * HALF; ga[nb_][bj] = *(const u32x4*)(gp + 6144); gb[nb_][bj] = *(const u32x4*)(gp + 8192); } }
; #pragma unroll
;             for (int bj = 0; bj < 2; ++bj) { f32x4 a0, a1, b0, b1; unpack_bf16x8(ga[cb][bj], a0, a1); unpack_bf16x8(gb[cb][bj], b0, b1);
; #pragma unroll
;                 for (int j = 0; j < 4; ++j) { a0[j] = a0[j] * __builtin_amdgcn_rcpf(fmaxf(b0[j], 1e-30f)); a1[j] = a1[j] * __builtin_amdgcn_rcpf(fmaxf(b1[j], 1e-30f)); }
;                 acc[ai][bj][m][0] = acc[ai][bj][m][0] * a0; acc[ai][bj][m][1] = acc[ai][bj][m][1] * a1; }
;             asm volatile("" ::: "memory"); }
	v_lshlrev_b32_e32 v188, 16, v136
	v_and_b32_e32 v189, 0xffff0000, v136
	v_lshlrev_b32_e32 v200, 16, v137
	v_and_b32_e32 v201, 0xffff0000, v137
	v_max_f32_e32 v188, v188, v188
	v_max_f32_e32 v189, v189, v189
	v_max_f32_e32 v200, v200, v200
	v_max_f32_e32 v201, v201, v201
	v_max_f32_e32 v188, 0xda24260, v188
	v_max_f32_e32 v189, 0xda24260, v189
	v_max_f32_e32 v200, 0xda24260, v200
	v_max_f32_e32 v201, 0xda24260, v201
	v_rcp_f32_e32 v188, v188
	v_rcp_f32_e32 v189, v189
	v_rcp_f32_e32 v200, v200
	v_rcp_f32_e32 v201, v201
	v_lshlrev_b32_e32 v204, 16, v132
	v_and_b32_e32 v205, 0xffff0000, v132
	v_lshlrev_b32_e32 v214, 16, v133
	v_and_b32_e32 v215, 0xffff0000, v133
	v_pk_mul_f32 v[188:189], v[188:189], v[204:205]
	v_pk_mul_f32 v[200:201], v[200:201], v[214:215]
	v_pk_mul_f32 v[64:65], v[64:65], v[188:189]
	v_pk_mul_f32 v[66:67], v[66:67], v[200:201]
	v_lshlrev_b32_e32 v188, 16, v138
	v_and_b32_e32 v189, 0xffff0000, v138
	v_lshlrev_b32_e32 v200, 16, v139
	v_and_b32_e32 v201, 0xffff0000, v139
	v_max_f32_e32 v188, v188, v188
	v_max_f32_e32 v189, v189, v189
	v_max_f32_e32 v200, v200, v200
	v_max_f32_e32 v201, v201, v201
	v_max_f32_e32 v188, 0xda24260, v188
	v_max_f32_e32 v189, 0xda24260, v189
	v_max_f32_e32 v200, 0xda24260, v200
	v_max_f32_e32 v201, 0xda24260, v201
	v_rcp_f32_e32 v188, v188
	v_rcp_f32_e32 v189, v189
	v_rcp_f32_e32 v200, v200
	v_rcp_f32_e32 v201, v201
	v_lshlrev_b32_e32 v204, 16, v134
	v_and_b32_e32 v205, 0xffff0000, v134
	v_lshlrev_b32_e32 v214, 16, v135
	v_and_b32_e32 v215, 0xffff0000, v135
	v_pk_mul_f32 v[188:189], v[188:189], v[204:205]
	v_pk_mul_f32 v[200:201], v[200:201], v[214:215]
	v_pk_mul_f32 v[60:61], v[60:61], v[188:189]
	v_pk_mul_f32 v[62:63], v[62:63], v[200:201]
	s_waitcnt vmcnt(12)
	v_lshlrev_b32_e32 v188, 16, v144
	v_and_b32_e32 v189, 0xffff0000, v144
	v_lshlrev_b32_e32 v200, 16, v145
	v_and_b32_e32 v201, 0xffff0000, v145
	v_max_f32_e32 v188, v188, v188
	v_max_f32_e32 v189, v189, v189
	v_max_f32_e32 v200, v200, v200
	v_max_f32_e32 v201, v201, v201
	v_max_f32_e32 v188, 0xda24260, v188
	v_max_f32_e32 v189, 0xda24260, v189
	v_max_f32_e32 v200, 0xda24260, v200
	v_max_f32_e32 v201, 0xda24260, v201
	v_rcp_f32_e32 v188, v188
	v_rcp_f32_e32 v189, v189
	v_rcp_f32_e32 v200, v200
	v_rcp_f32_e32 v201, v201
	v_lshlrev_b32_e32 v204, 16, v140
	v_and_b32_e32 v205, 0xffff0000, v140
	v_lshlrev_b32_e32 v214, 16, v141
	v_and_b32_e32 v215, 0xffff0000, v141
	v_pk_mul_f32 v[188:189], v[188:189], v[204:205]
	v_pk_mul_f32 v[200:201], v[200:201], v[214:215]
	v_pk_mul_f32 v[56:57], v[56:57], v[188:189]
	v_pk_mul_f32 v[58:59], v[58:59], v[200:201]
	v_lshlrev_b32_e32 v188, 16, v146
	v_and_b32_e32 v189, 0xffff0000, v146
	v_lshlrev_b32_e32 v200, 16, v147
	v_and_b32_e32 v201, 0xffff0000, v147
	v_max_f32_e32 v188, v188, v188
	v_max_f32_e32 v189, v189, v189
	v_max_f32_e32 v200, v200, v200
	v_max_f32_e32 v201, v201, v201
	v_max_f32_e32 v188, 0xda24260, v188
	v_max_f32_e32 v189, 0xda24260, v189
	v_max_f32_e32 v200, 0xda24260, v200
	v_max_f32_e32 v201, 0xda24260, v201
	v_rcp_f32_e32 v188, v188
	v_rcp_f32_e32 v189, v189
	v_rcp_f32_e32 v200, v200
	v_rcp_f32_e32 v201, v201
	v_lshlrev_b32_e32 v204, 16, v142
	v_and_b32_e32 v205, 0xffff0000, v142
	v_lshlrev_b32_e32 v214, 16, v143
	v_and_b32_e32 v215, 0xffff0000, v143
	v_pk_mul_f32 v[188:189], v[188:189], v[204:205]
	v_pk_mul_f32 v[200:201], v[200:201], v[214:215]
	v_pk_mul_f32 v[52:53], v[52:53], v[188:189]
	v_pk_mul_f32 v[54:55], v[54:55], v[200:201]
	s_waitcnt vmcnt(10)
	v_lshlrev_b32_e32 v188, 16, v152
	v_and_b32_e32 v189, 0xffff0000, v152
	v_lshlrev_b32_e32 v200, 16, v153
	v_and_b32_e32 v201, 0xffff0000, v153
	v_max_f32_e32 v188, v188, v188
	v_max_f32_e32 v189, v189, v189
	v_max_f32_e32 v200, v200, v200
	v_max_f32_e32 v201, v201, v201
	v_max_f32_e32 v188, 0xda24260, v188
	v_max_f32_e32 v189, 0xda24260, v189
	v_max_f32_e32 v200, 0xda24260, v200
	v_max_f32_e32 v201, 0xda24260, v201
	v_rcp_f32_e32 v188, v188
	v_rcp_f32_e32 v189, v189
	v_rcp_f32_e32 v200, v200
	v_rcp_f32_e32 v201, v201
	v_lshlrev_b32_e32 v204, 16, v148
	v_and_b32_e32 v205, 0xffff0000, v148
	v_lshlrev_b32_e32 v214, 16, v149
	v_and_b32_e32 v215, 0xffff0000, v149
	v_pk_mul_f32 v[188:189], v[188:189], v[204:205]
	v_pk_mul_f32 v[200:201], v[200:201], v[214:215]
	v_pk_mul_f32 v[48:49], v[48:49], v[188:189]
	v_pk_mul_f32 v[50:51], v[50:51], v[200:201]
	v_lshlrev_b32_e32 v188, 16, v154
	v_and_b32_e32 v189, 0xffff0000, v154
	v_lshlrev_b32_e32 v200, 16, v155
	v_and_b32_e32 v201, 0xffff0000, v155
	v_max_f32_e32 v188, v188, v188
	v_max_f32_e32 v189, v189, v189
	v_max_f32_e32 v200, v200, v200
	v_max_f32_e32 v201, v201, v201
	v_max_f32_e32 v188, 0xda24260, v188
	v_max_f32_e32 v189, 0xda24260, v189
	v_max_f32_e32 v200, 0xda24260, v200
	v_max_f32_e32 v201, 0xda24260, v201
	v_rcp_f32_e32 v188, v188
	v_rcp_f32_e32 v189, v189
	v_rcp_f32_e32 v200, v200
	v_rcp_f32_e32 v201, v201
	v_lshlrev_b32_e32 v204, 16, v150
	v_and_b32_e32 v205, 0xffff0000, v150
	v_lshlrev_b32_e32 v214, 16, v151
	v_and_b32_e32 v215, 0xffff0000, v151
	v_pk_mul_f32 v[188:189], v[188:189], v[204:205]
	v_pk_mul_f32 v[200:201], v[200:201], v[214:215]
	v_pk_mul_f32 v[44:45], v[44:45], v[188:189]
	v_pk_mul_f32 v[46:47], v[46:47], v[200:201]
	s_waitcnt vmcnt(8)
;     __device__ __forceinline__ void hook(f32x4 (&acc)[2][2][4][2], const Unit& u, int wr, int wc, int fr, int fq) const {
;     ...
;         for (int g = 0; g < 8; ++g) { const int ai = g >> 2, m = g & 3, cb = g & 1, nb_ = cb ^ 1;
;             if (g < 7) { const int an = (g + 1) >> 2, mn = (g + 1) & 3;
; #pragma unroll
;                 for (int bj = 0; bj < 2; ++bj) { const bf16_t* gp = G + (size_t)(row0 + an * HALF + mn * 16) * ldg + col0 + bj * HALF; ga[nb_][bj] = *(const u32x4*)(gp + 6144); gb[nb_][bj] = *(const u32x4*)(gp + 8192); } }
; #pragma unroll
;             for (int bj = 0; bj < 2; ++bj) { f32x4 a0, a1, b0, b1; unpack_bf16x8(ga[cb][bj], a0, a1); unpack_bf16x8(gb[cb][bj], b0, b1);
; #pragma unroll
;                 for (int j = 0; j < 4; ++j) { a0[j] = a0[j] * __builtin_amdgcn_rcpf(fmaxf(b0[j], 1e-30f)); a1[j] = a1[j] * __builtin_amdgcn_rcpf(fmaxf(b1[j], 1e-30f)); }
;                 acc[ai][bj][m][0] = acc[ai][bj][m][0] * a0; acc[ai][bj][m][1] = acc[ai][bj][m][1] * a1; }
;             asm volatile("" ::: "memory"); }
	v_lshlrev_b32_e32 v188, 16, v160
	v_and_b32_e32 v189, 0xffff0000, v160
	v_lshlrev_b32_e32 v200, 16, v161
	v_and_b32_e32 v201, 0xffff0000, v161
	v_max_f32_e32 v188, v188, v188
	v_max_f32_e32 v189, v189, v189
	v_max_f32_e32 v200, v200, v200
	v_max_f32_e32 v201, v201, v201
	v_max_f32_e32 v188, 0xda24260, v188
	v_max_f32_e32 v189, 0xda24260, v189
	v_max_f32_e32 v200, 0xda24260, v200
	v_max_f32_e32 v201, 0xda24260, v201
	v_rcp_f32_e32 v188, v188
	v_rcp_f32_e32 v189, v189
	v_rcp_f32_e32 v200, v200
	v_rcp_f32_e32 v201, v201
	v_lshlrev_b32_e32 v204, 16, v156
	v_and_b32_e32 v205, 0xffff0000, v156
	v_lshlrev_b32_e32 v214, 16, v157
	v_and_b32_e32 v215, 0xffff0000, v157
	v_pk_mul_f32 v[188:189], v[188:189], v[204:205]
	v_pk_mul_f32 v[200:201], v[200:201], v[214:215]
	v_pk_mul_f32 v[40:41], v[40:41], v[188:189]
	v_pk_mul_f32 v[42:43], v[42:43], v[200:201]
	v_lshlrev_b32_e32 v188, 16, v162
	v_and_b32_e32 v189, 0xffff0000, v162
	v_lshlrev_b32_e32 v200, 16, v163
	v_and_b32_e32 v201, 0xffff0000, v163
	v_max_f32_e32 v188, v188, v188
	v_max_f32_e32 v189, v189, v189
	v_max_f32_e32 v200, v200, v200
	v_max_f32_e32 v201, v201, v201
	v_max_f32_e32 v188, 0xda24260, v188
	v_max_f32_e32 v189, 0xda24260, v189
	v_max_f32_e32 v200, 0xda24260, v200
	v_max_f32_e32 v201, 0xda24260, v201
	v_rcp_f32_e32 v188, v188
	v_rcp_f32_e32 v189, v189
	v_rcp_f32_e32 v200, v200
	v_rcp_f32_e32 v201, v201
	v_lshlrev_b32_e32 v204, 16, v158
	v_and_b32_e32 v205, 0xffff0000, v158
	v_lshlrev_b32_e32 v214, 16, v159
	v_and_b32_e32 v215, 0xffff0000, v159
	v_pk_mul_f32 v[188:189], v[188:189], v[204:205]
	v_pk_mul_f32 v[200:201], v[200:201], v[214:215]
	v_pk_mul_f32 v[36:37], v[36:37], v[188:189]
	v_pk_mul_f32 v[38:39], v[38:39], v[200:201]
	s_waitcnt vmcnt(6)
	v_lshlrev_b32_e32 v188, 16, v210
	v_and_b32_e32 v189, 0xffff0000, v210
	v_lshlrev_b32_e32 v200, 16, v211
	v_and_b32_e32 v201, 0xffff0000, v211
	v_max_f32_e32 v188, v188, v188
	v_max_f32_e32 v189, v189, v189
	v_max_f32_e32 v200, v200, v200
	v_max_f32_e32 v201, v201, v201
	v_max_f32_e32 v188, 0xda24260, v188
	v_max_f32_e32 v189, 0xda24260, v189
	v_max_f32_e32 v200, 0xda24260, v200
	v_max_f32_e32 v201, 0xda24260, v201
	v_rcp_f32_e32 v188, v188
	v_rcp_f32_e32 v189, v189
	v_rcp_f32_e32 v200, v200
	v_rcp_f32_e32 v201, v201
	v_lshlrev_b32_e32 v204, 16, v196
	v_and_b32_e32 v205, 0xffff0000, v196
	v_lshlrev_b32_e32 v214, 16, v197
	v_and_b32_e32 v215, 0xffff0000, v197
	v_pk_mul_f32 v[188:189], v[188:189], v[204:205]
	v_pk_mul_f32 v[200:201], v[200:201], v[214:215]
	v_pk_mul_f32 v[32:33], v[32:33], v[188:189]
	v_pk_mul_f32 v[34:35], v[34:35], v[200:201]
	v_lshlrev_b32_e32 v188, 16, v212
	v_and_b32_e32 v189, 0xffff0000, v212
	v_lshlrev_b32_e32 v200, 16, v213
	v_and_b32_e32 v201, 0xffff0000, v213
	v_max_f32_e32 v188, v188, v188
	v_max_f32_e32 v189, v189, v189
	v_max_f32_e32 v200, v200, v200
	v_max_f32_e32 v201, v201, v201
	v_max_f32_e32 v188, 0xda24260, v188
	v_max_f32_e32 v189, 0xda24260, v189
	v_max_f32_e32 v200, 0xda24260, v200
	v_max_f32_e32 v201, 0xda24260, v201
	v_rcp_f32_e32 v188, v188
	v_rcp_f32_e32 v189, v189
	v_rcp_f32_e32 v200, v200
	v_rcp_f32_e32 v201, v201
	v_lshlrev_b32_e32 v204, 16, v198
	v_and_b32_e32 v205, 0xffff0000, v198
	v_lshlrev_b32_e32 v214, 16, v199
	v_and_b32_e32 v215, 0xffff0000, v199
	v_pk_mul_f32 v[188:189], v[188:189], v[204:205]
	v_pk_mul_f32 v[200:201], v[200:201], v[214:215]
	v_pk_mul_f32 v[28:29], v[28:29], v[188:189]
	v_pk_mul_f32 v[30:31], v[30:31], v[200:201]
	s_waitcnt vmcnt(4)
;     __device__ __forceinline__ void hook(f32x4 (&acc)[2][2][4][2], const Unit& u, int wr, int wc, int fr, int fq) const {
;     ...
;         for (int g = 0; g < 8; ++g) { const int ai = g >> 2, m = g & 3, cb = g & 1, nb_ = cb ^ 1;
;             if (g < 7) { const int an = (g + 1) >> 2, mn = (g + 1) & 3;
; #pragma unroll
;                 for (int bj = 0; bj < 2; ++bj) { const bf16_t* gp = G + (size_t)(row0 + an * HALF + mn * 16) * ldg + col0 + bj * HALF; ga[nb_][bj] = *(const u32x4*)(gp + 6144); gb[nb_][bj] = *(const u32x4*)(gp + 8192); } }
; #pragma unroll
;             for (int bj = 0; bj < 2; ++bj) { f32x4 a0, a1, b0, b1; unpack_bf16x8(ga[cb][bj], a0, a1); unpack_bf16x8(gb[cb][bj], b0, b1);
; #pragma unroll
;                 for (int j = 0; j < 4; ++j) { a0[j] = a0[j] * __builtin_amdgcn_rcpf(fmaxf(b0[j], 1e-30f)); a1[j] = a1[j] * __builtin_amdgcn_rcpf(fmaxf(b1[j], 1e-30f)); }
;                 acc[ai][bj][m][0] = acc[ai][bj][m][0] * a0; acc[ai][bj][m][1] = acc[ai][bj][m][1] * a1; }
;             asm volatile("" ::: "memory"); }
	v_lshlrev_b32_e32 v188, 16, v228
	v_and_b32_e32 v189, 0xffff0000, v228
	v_lshlrev_b32_e32 v200, 16, v229
	v_and_b32_e32 v201, 0xffff0000, v229
	v_max_f32_e32 v188, v188, v188
	v_max_f32_e32 v189, v189, v189
	v_max_f32_e32 v200, v200, v200
	v_max_f32_e32 v201, v201, v201
	v_max_f32_e32 v188, 0xda24260, v188
	v_max_f32_e32 v189, 0xda24260, v189
	v_max_f32_e32 v200, 0xda24260, v200
	v_max_f32_e32 v201, 0xda24260, v201
	v_rcp_f32_e32 v188, v188
	v_rcp_f32_e32 v189, v189
	v_rcp_f32_e32 v200, v200
	v_rcp_f32_e32 v201, v201
	v_lshlrev_b32_e32 v204, 16, v224
	v_and_b32_e32 v205, 0xffff0000, v224
	v_lshlrev_b32_e32 v214, 16, v225
	v_and_b32_e32 v215, 0xffff0000, v225
	v_pk_mul_f32 v[188:189], v[188:189], v[204:205]
	v_pk_mul_f32 v[200:201], v[200:201], v[214:215]
	v_pk_mul_f32 v[24:25], v[24:25], v[188:189]
	v_pk_mul_f32 v[26:27], v[26:27], v[200:201]
	v_lshlrev_b32_e32 v188, 16, v230
	v_and_b32_e32 v189, 0xffff0000, v230
	v_lshlrev_b32_e32 v200, 16, v231
	v_and_b32_e32 v201, 0xffff0000, v231
	v_max_f32_e32 v188, v188, v188
	v_max_f32_e32 v189, v189, v189
	v_max_f32_e32 v200, v200, v200
	v_max_f32_e32 v201, v201, v201
	v_max_f32_e32 v188, 0xda24260, v188
	v_max_f32_e32 v189, 0xda24260, v189
	v_max_f32_e32 v200, 0xda24260, v200
	v_max_f32_e32 v201, 0xda24260, v201
	v_rcp_f32_e32 v188, v188
	v_rcp_f32_e32 v189, v189
	v_rcp_f32_e32 v200, v200
	v_rcp_f32_e32 v201, v201
	v_lshlrev_b32_e32 v204, 16, v226
	v_and_b32_e32 v205, 0xffff0000, v226
	v_lshlrev_b32_e32 v214, 16, v227
	v_and_b32_e32 v215, 0xffff0000, v227
	v_pk_mul_f32 v[188:189], v[188:189], v[204:205]
	v_pk_mul_f32 v[200:201], v[200:201], v[214:215]
	v_pk_mul_f32 v[20:21], v[20:21], v[188:189]
	v_pk_mul_f32 v[22:23], v[22:23], v[200:201]
	s_waitcnt vmcnt(2)
	v_lshlrev_b32_e32 v188, 16, v236
	v_and_b32_e32 v189, 0xffff0000, v236
	v_lshlrev_b32_e32 v200, 16, v237
	v_and_b32_e32 v201, 0xffff0000, v237
	v_max_f32_e32 v188, v188, v188
	v_max_f32_e32 v189, v189, v189
	v_max_f32_e32 v200, v200, v200
	v_max_f32_e32 v201, v201, v201
	v_max_f32_e32 v188, 0xda24260, v188
	v_max_f32_e32 v189, 0xda24260, v189
	v_max_f32_e32 v200, 0xda24260, v200
	v_max_f32_e32 v201, 0xda24260, v201
	v_rcp_f32_e32 v188, v188
	v_rcp_f32_e32 v189, v189
	v_rcp_f32_e32 v200, v200
	v_rcp_f32_e32 v201, v201
	v_lshlrev_b32_e32 v204, 16, v232
	v_and_b32_e32 v205, 0xffff0000, v232
	v_lshlrev_b32_e32 v214, 16, v233
	v_and_b32_e32 v215, 0xffff0000, v233
	v_pk_mul_f32 v[188:189], v[188:189], v[204:205]
	v_pk_mul_f32 v[200:201], v[200:201], v[214:215]
	v_pk_mul_f32 v[16:17], v[16:17], v[188:189]
	v_pk_mul_f32 v[18:19], v[18:19], v[200:201]
	v_lshlrev_b32_e32 v188, 16, v238
	v_and_b32_e32 v189, 0xffff0000, v238
	v_lshlrev_b32_e32 v200, 16, v239
	v_and_b32_e32 v201, 0xffff0000, v239
	v_max_f32_e32 v188, v188, v188
	v_max_f32_e32 v189, v189, v189
	v_max_f32_e32 v200, v200, v200
	v_max_f32_e32 v201, v201, v201
	v_max_f32_e32 v188, 0xda24260, v188
	v_max_f32_e32 v189, 0xda24260, v189
	v_max_f32_e32 v200, 0xda24260, v200
	v_max_f32_e32 v201, 0xda24260, v201
	v_rcp_f32_e32 v188, v188
	v_rcp_f32_e32 v189, v189
	v_rcp_f32_e32 v200, v200
	v_rcp_f32_e32 v201, v201
	v_lshlrev_b32_e32 v204, 16, v234
	v_and_b32_e32 v205, 0xffff0000, v234
	v_lshlrev_b32_e32 v214, 16, v235
	v_and_b32_e32 v215, 0xffff0000, v235
	v_pk_mul_f32 v[188:189], v[188:189], v[204:205]
	v_pk_mul_f32 v[200:201], v[200:201], v[214:215]
	v_pk_mul_f32 v[12:13], v[12:13], v[188:189]
	v_pk_mul_f32 v[14:15], v[14:15], v[200:201]
	s_waitcnt vmcnt(0)
	v_lshlrev_b32_e32 v188, 16, v244
	v_and_b32_e32 v189, 0xffff0000, v244
	v_lshlrev_b32_e32 v200, 16, v245
	v_and_b32_e32 v201, 0xffff0000, v245
	v_max_f32_e32 v188, v188, v188
	v_max_f32_e32 v189, v189, v189
	v_max_f32_e32 v200, v200, v200
	v_max_f32_e32 v201, v201, v201
	v_max_f32_e32 v188, 0xda24260, v188
	v_max_f32_e32 v189, 0xda24260, v189
	v_max_f32_e32 v200, 0xda24260, v200
	v_max_f32_e32 v201, 0xda24260, v201
	v_rcp_f32_e32 v188, v188
	v_rcp_f32_e32 v189, v189
	v_rcp_f32_e32 v200, v200
	v_rcp_f32_e32 v201, v201
	v_lshlrev_b32_e32 v204, 16, v240
	v_and_b32_e32 v205, 0xffff0000, v240
	v_lshlrev_b32_e32 v214, 16, v241
	v_and_b32_e32 v215, 0xffff0000, v241
	v_pk_mul_f32 v[188:189], v[188:189], v[204:205]
	v_pk_mul_f32 v[200:201], v[200:201], v[214:215]
	v_pk_mul_f32 v[8:9], v[8:9], v[188:189]
	v_pk_mul_f32 v[10:11], v[10:11], v[200:201]
	v_lshlrev_b32_e32 v188, 16, v246
	v_and_b32_e32 v189, 0xffff0000, v246
	v_lshlrev_b32_e32 v200, 16, v247
	v_and_b32_e32 v201, 0xffff0000, v247
	v_max_f32_e32 v188, v188, v188
	v_max_f32_e32 v189, v189, v189
	v_max_f32_e32 v200, v200, v200
	v_max_f32_e32 v201, v201, v201
	v_max_f32_e32 v188, 0xda24260, v188
	v_max_f32_e32 v189, 0xda24260, v189
	v_max_f32_e32 v200, 0xda24260, v200
	v_max_f32_e32 v201, 0xda24260, v201
	v_rcp_f32_e32 v188, v188
	v_rcp_f32_e32 v189, v189
	v_rcp_f32_e32 v200, v200
	v_rcp_f32_e32 v201, v201
	v_lshlrev_b32_e32 v204, 16, v242
	v_and_b32_e32 v205, 0xffff0000, v242
	v_lshlrev_b32_e32 v214, 16, v243
	v_and_b32_e32 v215, 0xffff0000, v243
	v_pk_mul_f32 v[188:189], v[188:189], v[204:205]
	v_pk_mul_f32 v[200:201], v[200:201], v[214:215]
	v_pk_mul_f32 v[4:5], v[4:5], v[188:189]
	v_pk_mul_f32 v[6:7], v[6:7], v[200:201]
	s_branch .LBB0_754
